# P0: unified LDS-DMA pipelined weight transposes + convert_x loads hoisted
# baseline (speedup 1.0000x reference)
; #define LAS __attribute__((address_space(3)))
;     ...
;     const int tid = threadIdx.x; const int ntk = K / 64, ntn = Ndst / 64;
;     for (int t = blockIdx.x; t < ntk * ntn; t += gridDim.x) {
;         const int tn = t / ntk, tk = t - tn * ntk; const int n0 = tn * 64, k0 = tk * 64;
;         int s0 = n0, nvalid = 64;
;         if (kind == 1) { if (n0 < 3072) s0 = n0; else if (n0 < 7680) s0 = n0 + 16; else if (n0 == 7680) { s0 = 3072; nvalid = 16; } else { s0 = 0; nvalid = 0; } }
;         else if (kind == 2) { const int pn = n0 >> 8, j0 = n0 & 255; s0 = (j0 < 128) ? pn * 128 + j0 : DFF + pn * 128 + (j0 - 128); }
; #pragma unroll
;         for (int i = 0; i < 2; ++i) { const int idx = tid + 512 * i, kk = idx >> 4, n4 = idx & 15;
;             f32x4 v = {0.f, 0.f, 0.f, 0.f};
;             if (n4 * 4 < nvalid) v = *(const f32x4*)(src + (size_t)(k0 + kk) * Nsrc + s0 + n4 * 4);
;             const float gg = gain ? gain[k0 + kk] : 1.0f;
; #pragma unroll
;             for (int j = 0; j < 4; ++j) tile[kk * 65 + n4 * 4 + j] = v[j] * gg; }
;         __syncthreads();
;         { const int n = tid >> 3, k8 = tid & 7; float f[8];
; #pragma unroll
;             for (int j = 0; j < 8; ++j) f[j] = tile[(k8 * 8 + j) * 65 + n];
;             u32x4 w; w.x = pk_bf16(f[0], f[1]); w.y = pk_bf16(f[2], f[3]); w.z = pk_bf16(f[4], f[5]); w.w = pk_bf16(f[6], f[7]);
;             *(u32x4*)(dst + (size_t)(n0 + n) * ldd + koff + k0 + k8 * 8) = w; }
; __global__ void __launch_bounds__(512, 2) fwd_megakernel(Params p) {
;     ...
;     bf16_t* WIN = (bf16_t*)(ws + WS_WIN); bf16_t* WA = (bf16_t*)(ws + WS_WA); bf16_t* WB = (bf16_t*)(ws + WS_WB); bf16_t* WOUT = (bf16_t*)(ws + WS_WOUT);
;     bf16_t* WFIN = (bf16_t*)(ws + WS_WFIN); bf16_t* WFOUT = (bf16_t*)(ws + WS_WFOUT); bf16_t* WGLU = (bf16_t*)(ws + WS_WGLU);
;     bf16_t* XB = (bf16_t*)(ws + WS_XB); bf16_t* MIX = (bf16_t*)(ws + WS_Q); bf16_t* HID = (bf16_t*)(ws + WS_PROJ);
;     float* RSTD1 = (float*)(ws + WS_RSTD1); unsigned long long* SSQ2 = (unsigned long long*)(ws + WS_SSQ2); unsigned long long* SSQ3 = (unsigned long long*)(ws + WS_SSQ3);
;     if (IN(0)) {
;         LAS float* tile = (LAS float*)lds;
;         transpose_job(tile, p.w_in, WIN, p.norm1_g, 2048, 7696, NIN, 1);
;         transpose_job(tile, p.w_fin, WFIN, p.norm2_g, 2048, 2 * DFF, 2 * DFF, 2);
;         transpose_job(tile, p.w_fout, WFOUT, nullptr, DFF, 2048, 2048, 0);
.LBB0_17:
	s_load_dwordx16 s[4:19], s[0:1], 0x40
	s_waitcnt lgkmcnt(0)
	v_writelane_b32 v246, s4, 6
	s_nop 1
	v_writelane_b32 v246, s5, 7
	v_writelane_b32 v246, s6, 8
	v_writelane_b32 v246, s7, 9
	v_writelane_b32 v246, s8, 10
	v_writelane_b32 v246, s9, 11
	v_writelane_b32 v246, s10, 12
	v_writelane_b32 v246, s11, 13
	v_writelane_b32 v246, s12, 14
	v_writelane_b32 v246, s13, 15
	v_writelane_b32 v246, s14, 16
	v_writelane_b32 v246, s15, 17
	v_writelane_b32 v246, s16, 18
	v_writelane_b32 v246, s17, 19
	v_writelane_b32 v246, s18, 20
	v_writelane_b32 v246, s19, 21
	s_load_dwordx16 s[4:19], s[0:1], 0x80
	s_waitcnt lgkmcnt(0)
	v_writelane_b32 v246, s4, 22
	s_nop 1
	v_writelane_b32 v246, s5, 23
	v_writelane_b32 v246, s6, 24
	v_writelane_b32 v246, s7, 25
	v_writelane_b32 v246, s8, 26
	v_writelane_b32 v246, s9, 27
	v_writelane_b32 v246, s10, 28
	v_writelane_b32 v246, s11, 29
	v_writelane_b32 v246, s12, 30
	v_writelane_b32 v246, s13, 31
	v_writelane_b32 v246, s14, 32
	v_writelane_b32 v246, s15, 33
	v_writelane_b32 v246, s16, 34
	v_writelane_b32 v246, s17, 35
	v_writelane_b32 v246, s18, 36
	v_writelane_b32 v246, s19, 37
	s_add_u32 s8, s36, 0x23c0000
	s_addc_u32 s9, s37, 0
	s_add_u32 s0, s36, 0x42c0000
	s_addc_u32 s1, s37, 0
	v_writelane_b32 v246, s0, 38
	s_nop 1
	v_writelane_b32 v246, s1, 39
	s_add_u32 s0, s36, 0x48c0000
	s_addc_u32 s1, s37, 0
	v_writelane_b32 v246, s0, 40
	s_nop 1
	v_writelane_b32 v246, s1, 41
	s_add_u32 s0, s36, 0x50c0000
	s_addc_u32 s1, s37, 0
	v_writelane_b32 v246, s0, 42
	s_nop 1
	v_writelane_b32 v246, s1, 43
	s_add_u32 s0, s36, 0x7cc0000
	s_addc_u32 s1, s37, 0
	s_add_u32 s88, s36, 0x92c0000
	v_writelane_b32 v246, s0, 44
	s_addc_u32 s89, s37, 0
	s_nop 0
	v_writelane_b32 v246, s1, 45
	s_add_u32 s0, s36, 0x9340000
	s_addc_u32 s1, s37, 0
	v_writelane_b32 v246, s0, 46
	s_cmp_lt_i32 s38, 1
	s_nop 0
	v_writelane_b32 v246, s1, 47
	s_cselect_b64 s[0:1], -1, 0
	s_cmp_gt_i32 s39, 0
	s_cselect_b64 s[2:3], -1, 0
	s_and_b64 s[6:7], s[0:1], s[2:3]
	s_andn2_b64 vcc, exec, s[6:7]
	s_cbranch_vccnz .LBB0_67
	v_and_b32_e32 v1, 63, v220
	v_lshrrev_b32_e32 v2, 6, v220
	v_lshrrev_b32_e32 v3, 4, v1
	v_and_b32_e32 v4, 15, v1
	v_readfirstlane_b32 s53, v2
	v_lshl_add_u32 v3, v2, 2, v3
	v_lshrrev_b32_e32 v8, 3, v220
	v_and_b32_e32 v9, 7, v220
	v_add_u32_e32 v7, 32, v3
	s_lshr_b32 s54, s53, 1
	s_lshl_b32 s54, s54, 1
	s_or_b32 s55, s54, 8
	s_lshl_b32 s53, s53, 10
	v_xor_b32_e32 v5, s54, v4
	v_xor_b32_e32 v6, s55, v4
	v_lshlrev_b32_e32 v5, 4, v5
	v_lshlrev_b32_e32 v6, 4, v6
	v_lshrrev_b32_e32 v10, 2, v8
	v_lshlrev_b32_e32 v11, 1, v9
	v_xor_b32_e32 v10, v10, v11
	v_lshlrev_b32_e32 v10, 4, v10
	v_and_b32_e32 v11, 3, v8
	v_lshl_add_u32 v10, v11, 2, v10
	v_lshl_add_u32 v10, v9, 11, v10
	v_lshlrev_b32_e32 v12, 5, v9
	v_lshlrev_b32_e32 v13, 4, v9
	s_mov_b32 s1, 0
	s_mov_b32 s3, s96
.Lp0_pro_loop:
	s_mov_b32 s40, s3
	s_mov_b32 s52, 2
	s_branch .Lp0_dec
.Lp0_ret_pro:
	v_mad_u32_u24 v17, v3, s12, v5
	v_mad_u32_u24 v18, v7, s12, v6
	s_lshl_b32 s25, s1, 14
	s_add_u32 s25, s25, s53
	s_mov_b32 m0, s25
	s_add_u32 s25, s25, 0x2000
	global_load_lds_dwordx4 v17, s[10:11]
	s_mov_b32 m0, s25
	s_nop 0
	global_load_lds_dwordx4 v18, s[10:11]
	s_add_u32 s3, s3, s62
	s_add_u32 s1, s1, 1
	s_cmp_lt_u32 s1, 3
	s_cbranch_scc1 .Lp0_pro_loop
	s_mov_b32 s1, 0
	s_mov_b32 s0, s96
	s_mov_b32 s2, 0
.Lp0_loop:
	s_mul_i32 s3, s62, 3
	s_add_u32 s3, s3, s0
	s_cmp_lt_u32 s3, 0x37c0
	s_cselect_b32 s54, 1, 0
	s_cbranch_scc0 .Lp0_nodec
	s_mov_b32 s40, s3
	s_mov_b32 s52, 0
	s_branch .Lp0_dec
.Lp0_ret_dma:
	s_mov_b64 s[22:23], s[10:11]
	s_mov_b32 s24, s12
.Lp0_nodec:
	s_mov_b32 s40, s0
	s_mov_b32 s52, 1
	s_branch .Lp0_dec
.Lp0_ret_cons:
	global_load_dwordx4 v[20:23], v12, s[18:19]
	global_load_dwordx4 v[24:27], v12, s[18:19] offset:16
	v_mad_u32_u24 v14, v8, s16, v13
	v_add_u32_e32 v15, s2, v10
	v_add_u32_e32 v16, 0x400, v15
	s_lshl_b32 s4, s62, 1
	s_add_u32 s4, s4, s0
	s_cmp_lt_u32 s4, 0x37c0
	s_cbranch_scc0 .Lp0_w_tail
	s_cmp_ge_u32 s1, 3
	s_cbranch_scc0 .Lp0_w_early
	s_waitcnt vmcnt(13)
	s_branch .Lp0_w_done
.Lp0_w_early:
	s_waitcnt vmcnt(6)
	s_branch .Lp0_w_done
.Lp0_w_tail:
	s_waitcnt vmcnt(2)
.Lp0_w_done:
	s_barrier
	s_cmp_eq_u32 s54, 0
	s_cbranch_scc1 .Lp0_nodma
	v_mad_u32_u24 v17, v3, s24, v5
	v_mad_u32_u24 v18, v7, s24, v6
	s_add_u32 s25, s1, 3
	s_and_b32 s25, s25, 3
	s_lshl_b32 s25, s25, 14
	s_add_u32 s25, s25, s53
	s_mov_b32 m0, s25
	s_add_u32 s25, s25, 0x2000
	global_load_lds_dwordx4 v17, s[22:23]
	s_mov_b32 m0, s25
	s_nop 0
	global_load_lds_dwordx4 v18, s[22:23]
	ds_read2_b32 v[28:29], v15 offset1:64
	ds_read2_b32 v[30:31], v15 offset0:128 offset1:192
	ds_read2_b32 v[32:33], v16 offset1:64
	ds_read2_b32 v[34:35], v16 offset0:128 offset1:192
	s_waitcnt vmcnt(2)
	s_branch .Lp0_cons
.Lp0_nodma:
	ds_read2_b32 v[28:29], v15 offset1:64
	ds_read2_b32 v[30:31], v15 offset0:128 offset1:192
	ds_read2_b32 v[32:33], v16 offset1:64
	ds_read2_b32 v[34:35], v16 offset0:128 offset1:192
	s_waitcnt vmcnt(0)
.Lp0_cons:
	s_waitcnt lgkmcnt(0)
	s_cmp_eq_u32 s20, 0
	s_cbranch_scc1 .Lp0_nomul
	v_mul_f32_e32 v28, v28, v20
	v_mul_f32_e32 v29, v29, v21
	v_mul_f32_e32 v30, v30, v22
	v_mul_f32_e32 v31, v31, v23
	v_mul_f32_e32 v32, v32, v24
	v_mul_f32_e32 v33, v33, v25
	v_mul_f32_e32 v34, v34, v26
	v_mul_f32_e32 v35, v35, v27
;     ...
;     const int tid = threadIdx.x; const int ntk = K / 64, ntn = Ndst / 64;
;     for (int t = blockIdx.x; t < ntk * ntn; t += gridDim.x) {
;         const int tn = t / ntk, tk = t - tn * ntk; const int n0 = tn * 64, k0 = tk * 64;
;         int s0 = n0, nvalid = 64;
;         if (kind == 1) { if (n0 < 3072) s0 = n0; else if (n0 < 7680) s0 = n0 + 16; else if (n0 == 7680) { s0 = 3072; nvalid = 16; } else { s0 = 0; nvalid = 0; } }
;         else if (kind == 2) { const int pn = n0 >> 8, j0 = n0 & 255; s0 = (j0 < 128) ? pn * 128 + j0 : DFF + pn * 128 + (j0 - 128); }
; #pragma unroll
;         for (int i = 0; i < 2; ++i) { const int idx = tid + 512 * i, kk = idx >> 4, n4 = idx & 15;
;             f32x4 v = {0.f, 0.f, 0.f, 0.f};
;             if (n4 * 4 < nvalid) v = *(const f32x4*)(src + (size_t)(k0 + kk) * Nsrc + s0 + n4 * 4);
;             const float gg = gain ? gain[k0 + kk] : 1.0f;
; #pragma unroll
;             for (int j = 0; j < 4; ++j) tile[kk * 65 + n4 * 4 + j] = v[j] * gg; }
;         __syncthreads();
;         { const int n = tid >> 3, k8 = tid & 7; float f[8];
; #pragma unroll
;             for (int j = 0; j < 8; ++j) f[j] = tile[(k8 * 8 + j) * 65 + n];
;             u32x4 w; w.x = pk_bf16(f[0], f[1]); w.y = pk_bf16(f[2], f[3]); w.z = pk_bf16(f[4], f[5]); w.w = pk_bf16(f[6], f[7]);
;             *(u32x4*)(dst + (size_t)(n0 + n) * ldd + koff + k0 + k8 * 8) = w; }
; __global__ void __launch_bounds__(512, 2) fwd_megakernel(Params p) {
;     ...
;         transpose_job(tile, p.w_in, WIN, p.norm1_g, 2048, 7696, NIN, 1);
;         transpose_job(tile, p.w_fin, WFIN, p.norm2_g, 2048, 2 * DFF, 2 * DFF, 2);
;         transpose_job(tile, p.w_fout, WFOUT, nullptr, DFF, 2048, 2048, 0);
;         transpose_job(tile, p.w_out, WOUT, nullptr, 2048, 2048, 2048, 0);
;         transpose_job(tile, p.w_ba, WA, nullptr, 1024, 2048, 2048, 0, KAB, 0);
;         transpose_job(tile, p.w_bb, WA, nullptr, 512, 2048, 2048, 0, KAB, 1024);
;         transpose_job(tile, p.w_glu, WGLU, nullptr, 512, 512, 512, 0);
.Lp0_nomul:
	v_cmp_gt_u32_e32 vcc, s21, v8
	v_cvt_pk_bf16_f32 v36, v28, v29
	v_cvt_pk_bf16_f32 v37, v30, v31
	v_cvt_pk_bf16_f32 v38, v32, v33
	v_cvt_pk_bf16_f32 v39, v34, v35
	s_nop 1
	v_cndmask_b32_e32 v36, 0, v36, vcc
	v_cndmask_b32_e32 v37, 0, v37, vcc
	v_cndmask_b32_e32 v38, 0, v38, vcc
	v_cndmask_b32_e32 v39, 0, v39, vcc
	global_store_dwordx4 v14, v[36:39], s[14:15]
	s_add_u32 s0, s0, s62
	s_add_u32 s1, s1, 1
	s_and_b32 s2, s1, 3
	s_lshl_b32 s2, s2, 14
	s_cmp_lt_u32 s0, 0x37c0
	s_cbranch_scc1 .Lp0_loop
	s_branch .Lp0_done
.Lp0_dec:
	s_mov_b32 s21, 64
	s_mov_b32 s20, 0
	s_mov_b64 s[18:19], s[66:67]
	s_mov_b32 s45, 0x800
	s_cmp_lt_u32 s40, 0xf80
	s_cbranch_scc0 .Lp0_dec_n0
	s_lshr_b32 s41, s40, 5
	s_and_b32 s42, s40, 31
	s_lshl_b32 s43, s41, 6
	s_add_u32 s44, s43, 16
	s_cmp_lt_u32 s43, 0xc00
	s_cselect_b32 s44, s43, s44
	s_cmp_lt_u32 s43, 0x1e00
	s_cbranch_scc1 .Lp0_dec0_ok
	s_cmp_eq_u32 s43, 0x1e00
	s_cselect_b32 s44, 0xc00, 0
	s_cselect_b32 s21, 16, 0
.Lp0_dec0_ok:
	s_mov_b32 s45, 0x1e10
	s_mov_b32 s46, 0x800
	s_mov_b64 s[48:49], s[68:69]
	s_mov_b64 s[50:51], s[8:9]
	s_mov_b32 s20, 1
	s_branch .Lp0_dec_common
.Lp0_dec_n0:
	s_cmp_lt_u32 s40, 0x2580
	s_cbranch_scc0 .Lp0_dec_n1
	s_sub_u32 s41, s40, 0xf80
	s_and_b32 s42, s41, 31
	s_lshr_b32 s41, s41, 5
	s_lshl_b32 s43, s41, 6
	s_lshr_b32 s44, s41, 2
	s_lshl_b32 s44, s44, 7
	s_and_b32 s47, s41, 3
	s_lshl_b32 s47, s47, 6
	s_add_u32 s44, s44, s47
	s_add_u32 s26, s44, 0x1580
	s_cmp_lt_u32 s47, 0x80
	s_cselect_b32 s44, s44, s26
	s_mov_b32 s45, 0x2c00
	s_mov_b32 s46, 0x800
	v_readlane_b32 s48, v246, 30
	v_readlane_b32 s49, v246, 31
	v_readlane_b32 s50, v246, 42
	v_readlane_b32 s51, v246, 43
	v_readlane_b32 s18, v246, 28
	v_readlane_b32 s19, v246, 29
	s_mov_b32 s20, 1
	s_branch .Lp0_dec_common
.Lp0_dec_n1:
	s_cmp_lt_u32 s40, 0x3080
	s_cbranch_scc0 .Lp0_dec_n2
	s_sub_u32 s41, s40, 0x2580
	s_lshr_b32 s42, s41, 5
	s_and_b32 s41, s41, 31
	s_lshl_b32 s43, s41, 6
	s_mov_b32 s44, s43
	s_mov_b32 s46, 0x1600
	v_readlane_b32 s48, v246, 32
	v_readlane_b32 s49, v246, 33
	v_readlane_b32 s50, v246, 44
	v_readlane_b32 s51, v246, 45
	s_branch .Lp0_dec_common
.Lp0_dec_n2:
	s_cmp_lt_u32 s40, 0x3480
	s_cbranch_scc0 .Lp0_dec_n3
	s_sub_u32 s41, s40, 0x3080
	s_and_b32 s42, s41, 31
	s_lshr_b32 s41, s41, 5
	s_lshl_b32 s43, s41, 6
	s_mov_b32 s44, s43
	s_mov_b32 s46, 0x800
	v_readlane_b32 s48, v246, 26
	v_readlane_b32 s49, v246, 27
	v_readlane_b32 s50, v246, 40
	v_readlane_b32 s51, v246, 41
	s_branch .Lp0_dec_common
.Lp0_dec_n3:
	s_cmp_lt_u32 s40, 0x3680
	s_cbranch_scc0 .Lp0_dec_n4
	s_sub_u32 s41, s40, 0x3480
	s_and_b32 s42, s41, 15
	s_lshr_b32 s41, s41, 4
	s_lshl_b32 s43, s41, 6
	s_mov_b32 s44, s43
	s_mov_b32 s46, 0x600
	v_readlane_b32 s48, v246, 22
	v_readlane_b32 s49, v246, 23
	v_readlane_b32 s50, v246, 38
	v_readlane_b32 s51, v246, 39
	s_branch .Lp0_dec_common
.Lp0_dec_n4:
	s_cmp_lt_u32 s40, 0x3780
	s_cbranch_scc0 .Lp0_dec_n5
	s_sub_u32 s41, s40, 0x3680
	s_and_b32 s42, s41, 7
	s_lshr_b32 s41, s41, 3
	s_lshl_b32 s43, s41, 6
	s_mov_b32 s44, s43
	s_mov_b32 s46, 0x600
	v_readlane_b32 s48, v246, 24
	v_readlane_b32 s49, v246, 25
	v_readlane_b32 s50, v246, 38
	v_readlane_b32 s51, v246, 39
	s_nop 0
	s_add_u32 s50, s50, 0x800
	s_addc_u32 s51, s51, 0
	s_branch .Lp0_dec_common
.Lp0_dec_n5:
	s_sub_u32 s41, s40, 0x3780
	s_and_b32 s42, s41, 7
	s_lshr_b32 s41, s41, 3
	s_lshl_b32 s43, s41, 6
	s_mov_b32 s44, s43
	s_mov_b32 s45, 0x200
	s_mov_b32 s46, 0x200
	v_readlane_b32 s48, v246, 18
	v_readlane_b32 s49, v246, 19
	s_mov_b64 s[50:51], s[88:89]
.Lp0_dec_common:
	s_lshl_b32 s42, s42, 6
	s_mul_i32 s47, s42, s45
	s_add_u32 s47, s47, s44
	s_lshl_b32 s47, s47, 2
	s_add_u32 s10, s48, s47
	s_addc_u32 s11, s49, 0
	s_lshl_b32 s12, s45, 2
	s_mul_i32 s47, s43, s46
	s_add_u32 s47, s47, s42
	s_lshl_b32 s47, s47, 1
	s_add_u32 s14, s50, s47
	s_addc_u32 s15, s51, 0
	s_lshl_b32 s16, s46, 1
	s_mul_i32 s47, s42, s20
	s_lshl_b32 s47, s47, 2
	s_add_u32 s18, s18, s47
	s_addc_u32 s19, s19, 0
	s_cmp_eq_u32 s52, 0
	s_cbranch_scc1 .Lp0_ret_dma
	s_cmp_eq_u32 s52, 1
	s_cbranch_scc1 .Lp0_ret_cons
	s_branch .Lp0_ret_pro
.Lp0_done:
.LBB0_58:
	v_lshrrev_b32_e32 v0, 6, v220
	v_lshl_add_u32 v0, s96, 3, v0
	s_mov_b32 s0, 0x8000
	v_cmp_gt_i32_e32 vcc, s0, v0
	s_and_saveexec_b64 s[2:3], vcc
	s_cbranch_execz .LBB0_63
	v_mbcnt_lo_u32_b32 v2, -1, 0
	v_mbcnt_hi_u32_b32 v2, -1, v2
	v_and_b32_e32 v3, 64, v2
	v_add_u32_e32 v4, 64, v3
	v_xor_b32_e32 v5, 32, v2
	v_cmp_lt_i32_e64 s[0:1], v5, v4
	v_and_b32_e32 v1, 63, v220
	v_lshlrev_b32_e32 v6, 3, v1
	v_cndmask_b32_e64 v5, v2, v5, s[0:1]
	v_lshlrev_b32_e32 v10, 2, v5
	v_xor_b32_e32 v5, 16, v2
	v_cmp_lt_i32_e64 s[0:1], v5, v4
	v_mov_b32_e32 v3, 0
	v_or_b32_e32 v8, 0x400, v6
	v_cndmask_b32_e64 v5, v2, v5, s[0:1]
	v_lshlrev_b32_e32 v11, 2, v5
	v_xor_b32_e32 v5, 8, v2
	v_cmp_lt_i32_e64 s[0:1], v5, v4
	v_or_b32_e32 v16, 0x600, v6
	v_cmp_eq_u32_e32 vcc, 0, v1
	v_cndmask_b32_e64 v5, v2, v5, s[0:1]
	v_lshlrev_b32_e32 v12, 2, v5
	v_xor_b32_e32 v5, 4, v2
	v_cmp_lt_i32_e64 s[0:1], v5, v4
	s_lshl_b32 s12, s62, 3
	s_mov_b64 s[4:5], 0
	v_cndmask_b32_e64 v5, v2, v5, s[0:1]
	v_lshlrev_b32_e32 v13, 2, v5
	v_xor_b32_e32 v5, 2, v2
	v_cmp_lt_i32_e64 s[0:1], v5, v4
	v_mov_b32_e32 v7, v3
	v_mov_b32_e32 v9, v3
	v_cndmask_b32_e64 v5, v2, v5, s[0:1]
	v_lshlrev_b32_e32 v14, 2, v5
	v_xor_b32_e32 v5, 1, v2
	v_cmp_lt_i32_e64 s[0:1], v5, v4
	s_mov_b32 s13, 0x800000
	s_movk_i32 s14, 0x7fff
	v_cndmask_b32_e64 v2, v2, v5, s[0:1]
	v_readlane_b32 s0, v246, 46
	v_lshlrev_b32_e32 v15, 2, v2
	v_lshlrev_b32_e32 v2, 4, v1
	v_readlane_b32 s1, v246, 47
	s_nop 1
	v_lshl_add_u64 v[4:5], s[0:1], 0, v[2:3]
	v_lshlrev_b32_e32 v2, 2, v6
	v_lshlrev_b32_e32 v6, 2, v8
	v_lshlrev_b32_e32 v8, 2, v16
	v_mov_b32_e32 v16, 0x358637bd
	s_branch .LBB0_61

; __device__ __forceinline__ void convert_x(const float* __restrict__ x, bf16_t* xb, float* rstd) {
;     const int lane = threadIdx.x & 63, wv = threadIdx.x >> 6;
;     for (int row = blockIdx.x * 8 + wv; row < MTOK; row += gridDim.x * 8) {
;         const float* xr = x + (size_t)row * DM; bf16_t* o = xb + (size_t)row * DM; float s = 0.f;
; #pragma unroll
;         for (int i = 0; i < 4; ++i) { const int col = (i * 64 + lane) * 8; const f32x4 a = *(const f32x4*)(xr + col), b = *(const f32x4*)(xr + col + 4);
;             s += (a[0] * a[0] + a[1] * a[1]) + (a[2] * a[2] + a[3] * a[3]) + (b[0] * b[0] + b[1] * b[1]) + (b[2] * b[2] + b[3] * b[3]);
;             *(u32x4*)(o + col) = pack8(a, b); }
; #pragma unroll
;         for (int o2 = 32; o2 >= 1; o2 >>= 1) s += __shfl_xor(s, o2);
;         if (lane == 0) rstd[row] = rsqrtf(s * (1.0f / 2048.0f) + EPS);
;     }
; }
.LBB0_61:
	v_ashrrev_i32_e32 v1, 31, v0
	s_waitcnt lgkmcnt(0)
	v_lshlrev_b64 v[18:19], 13, v[0:1]
	v_lshl_add_u64 v[42:43], s[64:65], 0, v[18:19]
	v_lshl_add_u64 v[30:31], v[42:43], 0, v[2:3]
	v_lshl_add_u64 v[38:39], v[42:43], 0, v[6:7]
	v_lshl_add_u64 v[46:47], v[42:43], 0, v[8:9]
	global_load_dwordx4 v[52:55], v[30:31], off
	global_load_dwordx4 v[56:59], v[30:31], off offset:16
	global_load_dwordx4 v[60:63], v[30:31], off offset:2048
	global_load_dwordx4 v[64:67], v[30:31], off offset:2064
	global_load_dwordx4 v[68:71], v[38:39], off
	global_load_dwordx4 v[72:75], v[38:39], off offset:16
	global_load_dwordx4 v[76:79], v[46:47], off
	global_load_dwordx4 v[80:83], v[46:47], off offset:16
	v_lshlrev_b64 v[26:27], 12, v[0:1]
	v_lshl_add_u64 v[50:51], v[4:5], 0, v[26:27]
	s_waitcnt vmcnt(6)
	v_cvt_pk_bf16_f32 v26, v52, v53
	v_cvt_pk_bf16_f32 v27, v54, v55
	v_cvt_pk_bf16_f32 v28, v56, v57
	v_cvt_pk_bf16_f32 v29, v58, v59
	global_store_dwordx4 v[50:51], v[26:29], off
	v_mul_f32_e32 v17, v53, v53
	v_mul_f32_e32 v19, v55, v55
	v_fmac_f32_e32 v17, v52, v52
	v_fmac_f32_e32 v19, v54, v54
	v_mul_f32_e32 v21, v57, v57
	v_add_f32_e32 v17, v17, v19
	v_fmac_f32_e32 v21, v56, v56
	v_mul_f32_e32 v23, v59, v59
	v_add_f32_e32 v17, v17, v21
	v_fmac_f32_e32 v23, v58, v58
	v_add_f32_e32 v17, v23, v17
	s_waitcnt vmcnt(5)
	v_cvt_pk_bf16_f32 v34, v60, v61
	v_cvt_pk_bf16_f32 v35, v62, v63
	v_cvt_pk_bf16_f32 v36, v64, v65
	v_cvt_pk_bf16_f32 v37, v66, v67
	global_store_dwordx4 v[50:51], v[34:37], off offset:1024
	v_mul_f32_e32 v18, v61, v61
	v_mul_f32_e32 v19, v63, v63
	v_mul_f32_e32 v20, v65, v65
	v_fmac_f32_e32 v18, v60, v60
	v_fmac_f32_e32 v19, v62, v62
	v_mul_f32_e32 v21, v67, v67
	v_fmac_f32_e32 v20, v64, v64
	v_add_f32_e32 v18, v18, v19
	v_fmac_f32_e32 v21, v66, v66
	v_add_f32_e32 v18, v18, v20
	v_add_f32_e32 v18, v21, v18
	v_add_f32_e32 v17, v17, v18
	s_waitcnt vmcnt(4)
	v_cvt_pk_bf16_f32 v42, v68, v69
	v_cvt_pk_bf16_f32 v43, v70, v71
	v_cvt_pk_bf16_f32 v44, v72, v73
	v_cvt_pk_bf16_f32 v45, v74, v75
	global_store_dwordx4 v[50:51], v[42:45], off offset:2048
	v_mul_f32_e32 v18, v69, v69
	v_mul_f32_e32 v19, v71, v71
	v_mul_f32_e32 v20, v73, v73
	v_fmac_f32_e32 v18, v68, v68
	v_fmac_f32_e32 v19, v70, v70
	v_mul_f32_e32 v21, v75, v75
	v_fmac_f32_e32 v20, v72, v72
	v_add_f32_e32 v18, v18, v19
	v_fmac_f32_e32 v21, v74, v74
	v_add_f32_e32 v18, v18, v20
	v_add_f32_e32 v18, v21, v18
	v_add_f32_e32 v17, v17, v18
	s_waitcnt vmcnt(3)
	v_mul_f32_e32 v18, v77, v77
	v_mul_f32_e32 v19, v79, v79
	v_mul_f32_e32 v20, v81, v81
	v_fmac_f32_e32 v18, v76, v76
	v_fmac_f32_e32 v19, v78, v78
	v_mul_f32_e32 v21, v83, v83
	v_fmac_f32_e32 v20, v80, v80
	v_add_f32_e32 v18, v18, v19
	v_add_f32_e32 v18, v18, v20
	v_fmac_f32_e32 v21, v82, v82
	v_add_f32_e32 v18, v21, v18
	v_add_f32_e32 v17, v17, v18
	ds_bpermute_b32 v18, v10, v17
	v_cvt_pk_bf16_f32 v20, v76, v77
	v_cvt_pk_bf16_f32 v21, v78, v79
	v_cvt_pk_bf16_f32 v22, v80, v81
	v_cvt_pk_bf16_f32 v23, v82, v83
	s_waitcnt lgkmcnt(0)
	v_add_f32_e32 v17, v17, v18
	ds_bpermute_b32 v18, v11, v17
	global_store_dwordx4 v[50:51], v[20:23], off offset:3072
	s_waitcnt lgkmcnt(0)
	v_add_f32_e32 v17, v17, v18
	ds_bpermute_b32 v18, v12, v17
	s_waitcnt lgkmcnt(0)
	v_add_f32_e32 v17, v17, v18
	ds_bpermute_b32 v18, v13, v17
	s_waitcnt lgkmcnt(0)
	v_add_f32_e32 v17, v17, v18
	ds_bpermute_b32 v18, v14, v17
	s_waitcnt lgkmcnt(0)
	v_add_f32_e32 v17, v17, v18
	ds_bpermute_b32 v18, v15, v17
	s_and_saveexec_b64 s[10:11], vcc
	s_cbranch_execz .LBB0_60
	s_waitcnt lgkmcnt(0)
	v_add_f32_e32 v17, v17, v18
	v_fmamk_f32 v17, v17, 0x3a000000, v16
	v_mul_f32_e32 v18, 0x4b800000, v17
	v_cmp_gt_f32_e64 s[0:1], s13, v17
	s_nop 1
	v_cndmask_b32_e64 v17, v17, v18, s[0:1]
	v_rsq_f32_e32 v17, v17
	s_nop 0
	v_mul_f32_e32 v18, 0x45800000, v17
	v_cndmask_b32_e64 v17, v17, v18, s[0:1]
	v_lshl_add_u64 v[18:19], v[0:1], 2, s[36:37]
	global_store_dword v[18:19], v17, off
	s_branch .LBB0_60
